# baseline (speedup 1.0000x reference)
; __device__ __forceinline__ unsigned cvt_pk_bf16(float lo, float hi) { unsigned r; asm volatile("v_cvt_pk_bf16_f32 %0, %1, %2" : "=v"(r) : "v"(lo), "v"(hi)); return r; }
; #define GAS __attribute__((address_space(1)))
;     __device__ __forceinline__ void operator()(const f32x4 (&acc)[2][2][4][2], const Unit& u, int wr, int wc, int fr, int fq) const {
;     ...
;         for (int ai = 0; ai < 2; ++ai) {
;             u32x4 xo[4][2];
; #pragma unroll
;             for (int m = 0; m < 4; ++m)
; #pragma unroll
;                 for (int bj = 0; bj < 2; ++bj) xo[m][bj] = *(const GAS u32x4*)(xb + (size_t)(row0 + ai * 128 + m * 16) * DM + col0 + bj * 128);
;             asm volatile("" ::: "memory");
; #pragma unroll
;             for (int m = 0; m < 4; ++m) {
;                 const int row = row0 + ai * 128 + m * 16; float part = 0.f;
; #pragma unroll
;                 for (int bj = 0; bj < 2; ++bj) {
;                     bf16_t* xp = xb + (size_t)row * DM + col0 + bj * 128;
;                     const u32x4 q = xo[m][bj];
;                     f32x4 x0, x1;
;                     x0[0] = __uint_as_float(q.x << 16); x0[1] = __uint_as_float(q.x & 0xffff0000u); x0[2] = __uint_as_float(q.y << 16); x0[3] = __uint_as_float(q.y & 0xffff0000u);
;                     x1[0] = __uint_as_float(q.z << 16); x1[1] = __uint_as_float(q.z & 0xffff0000u); x1[2] = __uint_as_float(q.w << 16); x1[3] = __uint_as_float(q.w & 0xffff0000u);
;                     x0 = x0 + acc[ai][bj][m][0]; x1 = x1 + acc[ai][bj][m][1];
;                     part += (x0[0] * x0[0] + x0[1] * x0[1]) + (x0[2] * x0[2] + x0[3] * x0[3]) + (x1[0] * x1[0] + x1[1] * x1[1]) + (x1[2] * x1[2] + x1[3] * x1[3]);
;                     u32x4 w; w.x = cvt_pk_bf16(x0[0], x0[1]); w.y = cvt_pk_bf16(x0[2], x0[3]); w.z = cvt_pk_bf16(x1[0], x1[1]); w.w = cvt_pk_bf16(x1[2], x1[3]);
;                     *(GAS u32x4*)xp = w;
;                 }
;                 part += __shfl_xor(part, 16); part += __shfl_xor(part, 32);
;                 if (fq == 0) *(GAS float*)(ssacc + (size_t)row * 16 + u.pn * 4 + wc) = part;
;             }
.LBB0_197:
	v_lshl_or_b32 v162, s90, 8, v182
	v_lshl_add_u32 v166, s57, 8, v180
	v_ashrrev_i32_e32 v163, 31, v162
	v_lshlrev_b64 v[192:193], 1, v[162:163]
	v_ashrrev_i32_e32 v167, 31, v166
	v_lshl_add_u64 v[164:165], s[28:29], 0, v[192:193]
	v_lshlrev_b64 v[194:195], 11, v[166:167]
	v_lshl_add_u64 v[112:113], v[164:165], 0, v[194:195]
	global_load_dwordx4 v[184:187], v[112:113], off
	global_load_dwordx4 v[188:191], v[112:113], off offset:256
	v_or_b32_e32 v174, 16, v166
	v_ashrrev_i32_e32 v175, 31, v174
	v_or_b32_e32 v170, 32, v166
	v_lshlrev_b64 v[178:179], 11, v[174:175]
	v_ashrrev_i32_e32 v171, 31, v170
	v_or_b32_e32 v168, 48, v166
	v_lshl_add_u64 v[112:113], v[164:165], 0, v[178:179]
	v_lshlrev_b64 v[176:177], 11, v[170:171]
	v_ashrrev_i32_e32 v169, 31, v168
	global_load_dwordx4 v[148:151], v[112:113], off
	global_load_dwordx4 v[136:139], v[112:113], off offset:256
	v_lshl_add_u64 v[112:113], v[164:165], 0, v[176:177]
	v_lshlrev_b64 v[172:173], 11, v[168:169]
	global_load_dwordx4 v[124:127], v[112:113], off
	global_load_dwordx4 v[120:123], v[112:113], off offset:256
	v_lshl_add_u64 v[112:113], v[164:165], 0, v[172:173]
	global_load_dwordx4 v[116:119], v[112:113], off
	s_nop 0
	global_load_dwordx4 v[112:115], v[112:113], off offset:256
	v_mov_b32_e32 v243, 0
	v_add_u32_e32 v242, 0x80, v166
	v_lshlrev_b32_e32 v242, 11, v242
	v_lshl_add_u64 v[240:241], v[164:165], 0, v[242:243]
	global_load_dwordx4 v[198:201], v[240:241], off
	global_load_dwordx4 v[202:205], v[240:241], off offset:256
	v_add_u32_e32 v242, 0x90, v166
	v_lshlrev_b32_e32 v242, 11, v242
	v_lshl_add_u64 v[240:241], v[164:165], 0, v[242:243]
	global_load_dwordx4 v[206:209], v[240:241], off
	global_load_dwordx4 v[210:213], v[240:241], off offset:256
	v_add_u32_e32 v242, 0xa0, v166
	v_lshlrev_b32_e32 v242, 11, v242
	v_lshl_add_u64 v[240:241], v[164:165], 0, v[242:243]
	global_load_dwordx4 v[214:217], v[240:241], off
	global_load_dwordx4 v[222:225], v[240:241], off offset:256
	v_add_u32_e32 v242, 0xb0, v166
	v_lshlrev_b32_e32 v242, 11, v242
	v_lshl_add_u64 v[240:241], v[164:165], 0, v[242:243]
	global_load_dwordx4 v[226:229], v[240:241], off
	global_load_dwordx4 v[234:237], v[240:241], off offset:256
	v_lshl_add_u64 v[194:195], s[28:29], 0, v[194:195]
	v_lshl_add_u64 v[192:193], v[194:195], 0, v[192:193]
	s_lshl_b32 s64, s90, 2
	s_ashr_i32 s65, s64, 31
	s_waitcnt vmcnt(8)
	v_lshlrev_b32_e32 v194, 16, v184
	v_and_b32_e32 v195, 0xffff0000, v184
	v_lshlrev_b32_e32 v184, 16, v185
	v_and_b32_e32 v185, 0xffff0000, v185
	v_lshlrev_b32_e32 v196, 16, v186
	v_and_b32_e32 v197, 0xffff0000, v186
	v_lshlrev_b32_e32 v186, 16, v187
	v_and_b32_e32 v187, 0xffff0000, v187
	v_pk_add_f32 v[146:147], v[146:147], v[184:185]
	v_pk_add_f32 v[144:145], v[144:145], v[194:195]
	v_pk_add_f32 v[184:185], v[142:143], v[186:187]
	v_pk_add_f32 v[142:143], v[140:141], v[196:197]
	v_mul_f32_e32 v140, v145, v145
	v_mul_f32_e32 v141, v147, v147
	v_fmac_f32_e32 v140, v144, v144
	v_fmac_f32_e32 v141, v146, v146
	v_add_f32_e32 v140, v140, v141
	v_mul_f32_e32 v141, v143, v143
	v_fmac_f32_e32 v141, v142, v142
	v_add_f32_e32 v140, v141, v140
	v_mul_f32_e32 v141, v185, v185
	v_fmac_f32_e32 v141, v184, v184
	v_add_f32_e32 v186, v141, v140
	v_cvt_pk_bf16_f32 v140, v144, v145
	v_cvt_pk_bf16_f32 v141, v146, v147
	v_cvt_pk_bf16_f32 v142, v142, v143
	v_cvt_pk_bf16_f32 v143, v184, v185
	global_store_dwordx4 v[192:193], v[140:143], off
	v_lshlrev_b32_e32 v144, 16, v190
	v_and_b32_e32 v145, 0xffff0000, v190
	v_lshlrev_b32_e32 v140, 16, v188
	v_and_b32_e32 v141, 0xffff0000, v188
	v_lshlrev_b32_e32 v142, 16, v189
	v_and_b32_e32 v143, 0xffff0000, v189
	v_lshlrev_b32_e32 v146, 16, v191
	v_and_b32_e32 v147, 0xffff0000, v191
	v_pk_add_f32 v[134:135], v[134:135], v[142:143]
	v_pk_add_f32 v[132:133], v[132:133], v[140:141]
	v_pk_add_f32 v[140:141], v[130:131], v[146:147]
	v_pk_add_f32 v[130:131], v[128:129], v[144:145]
	v_mul_f32_e32 v128, v133, v133
	v_mul_f32_e32 v129, v135, v135
	v_fmac_f32_e32 v128, v132, v132
	v_fmac_f32_e32 v129, v134, v134
	v_add_f32_e32 v128, v128, v129
	v_mul_f32_e32 v129, v131, v131
	v_fmac_f32_e32 v129, v130, v130
	v_add_f32_e32 v128, v129, v128
	v_mul_f32_e32 v129, v141, v141
	v_fmac_f32_e32 v129, v140, v140
	v_add_f32_e32 v128, v129, v128
	v_add_f32_e32 v142, v186, v128
	v_cvt_pk_bf16_f32 v128, v132, v133
	v_cvt_pk_bf16_f32 v129, v134, v135
	v_cvt_pk_bf16_f32 v130, v130, v131
	v_cvt_pk_bf16_f32 v131, v140, v141
	global_store_dwordx4 v[192:193], v[128:131], off offset:256
	s_nop 1
	v_and_b32_e32 v129, 64, v244
	v_xor_b32_e32 v128, 16, v244
	v_add_u32_e32 v129, 64, v129
	v_cmp_lt_i32_e32 vcc, v128, v129
	v_xor_b32_e32 v131, 32, v244
	s_nop 0
	v_cndmask_b32_e32 v128, v244, v128, vcc
	v_lshlrev_b32_e32 v128, 2, v128
	ds_bpermute_b32 v130, v128, v142
	v_cmp_lt_i32_e32 vcc, v131, v129
	s_waitcnt lgkmcnt(0)
	v_add_f32_e32 v130, v142, v130
	v_cndmask_b32_e32 v129, v244, v131, vcc
	v_lshlrev_b32_e32 v129, 2, v129
	ds_bpermute_b32 v131, v129, v130
	s_and_saveexec_b64 s[38:39], s[6:7]
	s_cbranch_execz .LBB0_199
	s_waitcnt lgkmcnt(0)
	v_add_f32_e32 v132, v130, v131
	v_lshlrev_b64 v[130:131], 6, v[166:167]
	v_lshl_add_u64 v[130:131], s[30:31], 0, v[130:131]
	v_lshl_add_u64 v[130:131], s[64:65], 2, v[130:131]
	s_lshl_b32 s90, s61, 2
	v_lshl_add_u64 v[130:131], v[130:131], 0, s[90:91]
	global_store_dword v[130:131], v132, off

; __device__ __forceinline__ unsigned cvt_pk_bf16(float lo, float hi) { unsigned r; asm volatile("v_cvt_pk_bf16_f32 %0, %1, %2" : "=v"(r) : "v"(lo), "v"(hi)); return r; }
; #define GAS __attribute__((address_space(1)))
;     __device__ __forceinline__ void operator()(const f32x4 (&acc)[2][2][4][2], const Unit& u, int wr, int wc, int fr, int fq) const {
;     ...
;         for (int ai = 0; ai < 2; ++ai) {
;             u32x4 xo[4][2];
; #pragma unroll
;             for (int m = 0; m < 4; ++m)
; #pragma unroll
;                 for (int bj = 0; bj < 2; ++bj) xo[m][bj] = *(const GAS u32x4*)(xb + (size_t)(row0 + ai * 128 + m * 16) * DM + col0 + bj * 128);
;             asm volatile("" ::: "memory");
; #pragma unroll
;             for (int m = 0; m < 4; ++m) {
;                 const int row = row0 + ai * 128 + m * 16; float part = 0.f;
; #pragma unroll
;                 for (int bj = 0; bj < 2; ++bj) {
;                     bf16_t* xp = xb + (size_t)row * DM + col0 + bj * 128;
;                     const u32x4 q = xo[m][bj];
;                     f32x4 x0, x1;
;                     x0[0] = __uint_as_float(q.x << 16); x0[1] = __uint_as_float(q.x & 0xffff0000u); x0[2] = __uint_as_float(q.y << 16); x0[3] = __uint_as_float(q.y & 0xffff0000u);
;                     x1[0] = __uint_as_float(q.z << 16); x1[1] = __uint_as_float(q.z & 0xffff0000u); x1[2] = __uint_as_float(q.w << 16); x1[3] = __uint_as_float(q.w & 0xffff0000u);
;                     x0 = x0 + acc[ai][bj][m][0]; x1 = x1 + acc[ai][bj][m][1];
;                     part += (x0[0] * x0[0] + x0[1] * x0[1]) + (x0[2] * x0[2] + x0[3] * x0[3]) + (x1[0] * x1[0] + x1[1] * x1[1]) + (x1[2] * x1[2] + x1[3] * x1[3]);
;                     u32x4 w; w.x = cvt_pk_bf16(x0[0], x0[1]); w.y = cvt_pk_bf16(x0[2], x0[3]); w.z = cvt_pk_bf16(x1[0], x1[1]); w.w = cvt_pk_bf16(x1[2], x1[3]);
;                     *(GAS u32x4*)xp = w;
;                 }
;                 part += __shfl_xor(part, 16); part += __shfl_xor(part, 32);
;                 if (fq == 0) *(GAS float*)(ssacc + (size_t)row * 16 + u.pn * 4 + wc) = part;
;             }
.LBB0_205:
	s_or_b64 exec, exec, s[38:39]
	v_add_u32_e32 v104, 0x80, v166
	v_ashrrev_i32_e32 v105, 31, v104
	v_lshlrev_b64 v[106:107], 11, v[104:105]
	s_waitcnt lgkmcnt(0)
	v_lshl_add_u64 v[64:65], v[164:165], 0, v[106:107]
	v_add_u32_e32 v98, 0x90, v166
	v_ashrrev_i32_e32 v99, 31, v98
	v_add_u32_e32 v94, 0xa0, v166
	v_lshlrev_b64 v[102:103], 11, v[98:99]
	v_ashrrev_i32_e32 v95, 31, v94
	v_add_u32_e32 v92, 0xb0, v166
	v_lshl_add_u64 v[64:65], v[164:165], 0, v[102:103]
	v_lshlrev_b64 v[100:101], 11, v[94:95]
	v_ashrrev_i32_e32 v93, 31, v92
	v_lshl_add_u64 v[64:65], v[164:165], 0, v[100:101]
	v_lshlrev_b64 v[96:97], 11, v[92:93]
	v_lshl_add_u64 v[64:65], v[164:165], 0, v[96:97]
	s_nop 0
	v_lshl_add_u64 v[106:107], s[28:29], 0, v[106:107]
	v_lshl_add_u64 v[106:107], v[162:163], 1, v[106:107]
	s_waitcnt vmcnt(8)
	v_lshlrev_b32_e32 v112, 16, v198
	v_and_b32_e32 v113, 0xffff0000, v198
	v_lshlrev_b32_e32 v108, 16, v199
	v_and_b32_e32 v109, 0xffff0000, v199
	v_lshlrev_b32_e32 v114, 16, v200
	v_and_b32_e32 v115, 0xffff0000, v200
	v_lshlrev_b32_e32 v110, 16, v201
	v_and_b32_e32 v111, 0xffff0000, v201
	v_pk_add_f32 v[62:63], v[62:63], v[108:109]
	v_pk_add_f32 v[60:61], v[60:61], v[112:113]
	v_pk_add_f32 v[108:109], v[58:59], v[110:111]
	v_pk_add_f32 v[58:59], v[56:57], v[114:115]
	v_mul_f32_e32 v56, v61, v61
	v_mul_f32_e32 v57, v63, v63
	v_fmac_f32_e32 v56, v60, v60
	v_fmac_f32_e32 v57, v62, v62
	v_add_f32_e32 v56, v56, v57
	v_mul_f32_e32 v57, v59, v59
	v_fmac_f32_e32 v57, v58, v58
	v_add_f32_e32 v56, v57, v56
	v_mul_f32_e32 v57, v109, v109
	v_fmac_f32_e32 v57, v108, v108
	v_add_f32_e32 v110, v57, v56
	v_cvt_pk_bf16_f32 v56, v60, v61
	v_cvt_pk_bf16_f32 v57, v62, v63
	v_cvt_pk_bf16_f32 v58, v58, v59
	v_cvt_pk_bf16_f32 v59, v108, v109
	global_store_dwordx4 v[106:107], v[56:59], off
	s_waitcnt vmcnt(7)
	v_lshlrev_b32_e32 v60, 16, v204
	v_and_b32_e32 v61, 0xffff0000, v204
	v_lshlrev_b32_e32 v56, 16, v202
	v_and_b32_e32 v57, 0xffff0000, v202
	v_lshlrev_b32_e32 v58, 16, v203
	v_and_b32_e32 v59, 0xffff0000, v203
	v_lshlrev_b32_e32 v62, 16, v205
	v_and_b32_e32 v63, 0xffff0000, v205
	v_pk_add_f32 v[54:55], v[54:55], v[58:59]
	v_pk_add_f32 v[52:53], v[52:53], v[56:57]
	v_pk_add_f32 v[56:57], v[50:51], v[62:63]
	v_pk_add_f32 v[50:51], v[48:49], v[60:61]
	v_mul_f32_e32 v48, v53, v53
	v_mul_f32_e32 v49, v55, v55
	v_fmac_f32_e32 v48, v52, v52
	v_fmac_f32_e32 v49, v54, v54
	v_add_f32_e32 v48, v48, v49
	v_mul_f32_e32 v49, v51, v51
	v_fmac_f32_e32 v49, v50, v50
	v_add_f32_e32 v48, v49, v48
	v_mul_f32_e32 v49, v57, v57
	v_fmac_f32_e32 v49, v56, v56
	v_add_f32_e32 v48, v49, v48
	v_add_f32_e32 v58, v110, v48
	v_cvt_pk_bf16_f32 v48, v52, v53
	v_cvt_pk_bf16_f32 v49, v54, v55
	v_cvt_pk_bf16_f32 v50, v50, v51
	v_cvt_pk_bf16_f32 v51, v56, v57
	global_store_dwordx4 v[106:107], v[48:51], off offset:256
	ds_bpermute_b32 v48, v128, v58
	s_waitcnt lgkmcnt(0)
	v_add_f32_e32 v48, v58, v48
	ds_bpermute_b32 v49, v129, v48
	s_and_saveexec_b64 s[38:39], s[6:7]
	s_cbranch_execz .LBB0_207
	s_waitcnt lgkmcnt(0)
	v_add_f32_e32 v50, v48, v49
	v_lshlrev_b64 v[48:49], 6, v[104:105]
	v_lshl_add_u64 v[48:49], s[30:31], 0, v[48:49]
	v_lshl_add_u64 v[48:49], s[64:65], 2, v[48:49]
	s_lshl_b32 s90, s61, 2
	v_lshl_add_u64 v[48:49], v[48:49], 0, s[90:91]
	global_store_dword v[48:49], v50, off
.LBB0_207:
	s_or_b64 exec, exec, s[38:39]
	s_waitcnt vmcnt(7)
	v_lshlrev_b32_e32 v50, 16, v206
	v_and_b32_e32 v51, 0xffff0000, v206
	v_lshlrev_b32_e32 v52, 16, v207
	v_and_b32_e32 v53, 0xffff0000, v207
	v_lshlrev_b32_e32 v54, 16, v208
	v_and_b32_e32 v55, 0xffff0000, v208
	v_lshlrev_b32_e32 v56, 16, v209
	v_and_b32_e32 v57, 0xffff0000, v209
	v_pk_add_f32 v[46:47], v[46:47], v[52:53]
	v_pk_add_f32 v[44:45], v[44:45], v[50:51]
	v_pk_add_f32 v[50:51], v[42:43], v[56:57]
	v_pk_add_f32 v[42:43], v[40:41], v[54:55]
	v_mul_f32_e32 v40, v45, v45
	v_mul_f32_e32 v41, v47, v47
	v_fmac_f32_e32 v40, v44, v44
	v_fmac_f32_e32 v41, v46, v46
	v_add_f32_e32 v40, v40, v41
	v_mul_f32_e32 v41, v43, v43
	v_fmac_f32_e32 v41, v42, v42
	v_add_f32_e32 v40, v41, v40
	v_mul_f32_e32 v41, v51, v51
	v_fmac_f32_e32 v41, v50, v50
	v_add_f32_e32 v56, v41, v40
	v_cvt_pk_bf16_f32 v40, v44, v45
	v_cvt_pk_bf16_f32 v41, v46, v47
	s_waitcnt vmcnt(6)
	v_lshlrev_b32_e32 v44, 16, v210
	v_and_b32_e32 v45, 0xffff0000, v210
	v_lshlrev_b32_e32 v46, 16, v211
	v_and_b32_e32 v47, 0xffff0000, v211
	v_lshlrev_b32_e32 v52, 16, v212
	v_and_b32_e32 v53, 0xffff0000, v212
	v_pk_add_f32 v[38:39], v[38:39], v[46:47]
	v_pk_add_f32 v[36:37], v[36:37], v[44:45]
	v_pk_add_f32 v[46:47], v[32:33], v[52:53]
	v_mul_f32_e32 v32, v37, v37
	v_mul_f32_e32 v33, v39, v39
	v_fmac_f32_e32 v32, v36, v36
	v_fmac_f32_e32 v33, v38, v38
	v_lshlrev_b32_e32 v54, 16, v213
	v_and_b32_e32 v55, 0xffff0000, v213
	v_add_f32_e32 v32, v32, v33
	v_mul_f32_e32 v33, v47, v47
	v_pk_add_f32 v[44:45], v[34:35], v[54:55]
	v_fmac_f32_e32 v33, v46, v46
	v_add_f32_e32 v32, v33, v32
	v_mul_f32_e32 v33, v45, v45
	v_fmac_f32_e32 v33, v44, v44
	v_add_f32_e32 v32, v33, v32
	v_add_f32_e32 v32, v56, v32
	ds_bpermute_b32 v33, v128, v32
	s_waitcnt lgkmcnt(1)
	v_lshl_add_u64 v[48:49], s[28:29], 0, v[102:103]
	v_lshl_add_u64 v[48:49], v[162:163], 1, v[48:49]
	v_cvt_pk_bf16_f32 v42, v42, v43
	v_cvt_pk_bf16_f32 v43, v50, v51
	s_waitcnt lgkmcnt(0)
	v_add_f32_e32 v32, v32, v33
	ds_bpermute_b32 v33, v129, v32
	global_store_dwordx4 v[48:49], v[40:43], off
	v_cvt_pk_bf16_f32 v34, v36, v37
	v_cvt_pk_bf16_f32 v35, v38, v39
	v_cvt_pk_bf16_f32 v36, v46, v47
	v_cvt_pk_bf16_f32 v37, v44, v45
	global_store_dwordx4 v[48:49], v[34:37], off offset:256
	s_and_saveexec_b64 s[38:39], s[6:7]
	s_cbranch_execz .LBB0_209
	s_waitcnt lgkmcnt(0)
	v_add_f32_e32 v34, v32, v33
	v_lshlrev_b64 v[32:33], 6, v[98:99]
	v_lshl_add_u64 v[32:33], s[30:31], 0, v[32:33]
	v_lshl_add_u64 v[32:33], s[64:65], 2, v[32:33]
	s_lshl_b32 s90, s61, 2
	v_lshl_add_u64 v[32:33], v[32:33], 0, s[90:91]
	global_store_dword v[32:33], v34, off
; __device__ __forceinline__ unsigned cvt_pk_bf16(float lo, float hi) { unsigned r; asm volatile("v_cvt_pk_bf16_f32 %0, %1, %2" : "=v"(r) : "v"(lo), "v"(hi)); return r; }
; #define GAS __attribute__((address_space(1)))
;     __device__ __forceinline__ void operator()(const f32x4 (&acc)[2][2][4][2], const Unit& u, int wr, int wc, int fr, int fq) const {
;     ...
;             for (int m = 0; m < 4; ++m) {
;                 const int row = row0 + ai * 128 + m * 16; float part = 0.f;
; #pragma unroll
;                 for (int bj = 0; bj < 2; ++bj) {
;                     bf16_t* xp = xb + (size_t)row * DM + col0 + bj * 128;
;                     const u32x4 q = xo[m][bj];
;                     f32x4 x0, x1;
;                     x0[0] = __uint_as_float(q.x << 16); x0[1] = __uint_as_float(q.x & 0xffff0000u); x0[2] = __uint_as_float(q.y << 16); x0[3] = __uint_as_float(q.y & 0xffff0000u);
;                     x1[0] = __uint_as_float(q.z << 16); x1[1] = __uint_as_float(q.z & 0xffff0000u); x1[2] = __uint_as_float(q.w << 16); x1[3] = __uint_as_float(q.w & 0xffff0000u);
;                     x0 = x0 + acc[ai][bj][m][0]; x1 = x1 + acc[ai][bj][m][1];
;                     part += (x0[0] * x0[0] + x0[1] * x0[1]) + (x0[2] * x0[2] + x0[3] * x0[3]) + (x1[0] * x1[0] + x1[1] * x1[1]) + (x1[2] * x1[2] + x1[3] * x1[3]);
;                     u32x4 w; w.x = cvt_pk_bf16(x0[0], x0[1]); w.y = cvt_pk_bf16(x0[2], x0[3]); w.z = cvt_pk_bf16(x1[0], x1[1]); w.w = cvt_pk_bf16(x1[2], x1[3]);
;                     *(GAS u32x4*)xp = w;
;                 }
;                 part += __shfl_xor(part, 16); part += __shfl_xor(part, 32);
;                 if (fq == 0) *(GAS float*)(ssacc + (size_t)row * 16 + u.pn * 4 + wc) = part;
;             }
.LBB0_209:
	s_or_b64 exec, exec, s[38:39]
	s_waitcnt vmcnt(7)
	v_lshlrev_b32_e32 v34, 16, v214
	v_and_b32_e32 v35, 0xffff0000, v214
	v_lshlrev_b32_e32 v36, 16, v215
	v_and_b32_e32 v37, 0xffff0000, v215
	v_lshlrev_b32_e32 v38, 16, v216
	v_and_b32_e32 v39, 0xffff0000, v216
	v_lshlrev_b32_e32 v40, 16, v217
	v_and_b32_e32 v41, 0xffff0000, v217
	v_pk_add_f32 v[30:31], v[30:31], v[36:37]
	v_pk_add_f32 v[28:29], v[28:29], v[34:35]
	v_pk_add_f32 v[34:35], v[26:27], v[40:41]
	v_pk_add_f32 v[26:27], v[24:25], v[38:39]
	v_mul_f32_e32 v24, v29, v29
	v_mul_f32_e32 v25, v31, v31
	v_fmac_f32_e32 v24, v28, v28
	v_fmac_f32_e32 v25, v30, v30
	v_add_f32_e32 v24, v24, v25
	v_mul_f32_e32 v25, v27, v27
	v_fmac_f32_e32 v25, v26, v26
	v_add_f32_e32 v24, v25, v24
	v_mul_f32_e32 v25, v35, v35
	v_fmac_f32_e32 v25, v34, v34
	v_add_f32_e32 v40, v25, v24
	v_cvt_pk_bf16_f32 v24, v28, v29
	v_cvt_pk_bf16_f32 v25, v30, v31
	s_waitcnt vmcnt(6)
	v_lshlrev_b32_e32 v28, 16, v222
	v_and_b32_e32 v29, 0xffff0000, v222
	v_lshlrev_b32_e32 v30, 16, v223
	v_and_b32_e32 v31, 0xffff0000, v223
	v_lshlrev_b32_e32 v36, 16, v224
	v_and_b32_e32 v37, 0xffff0000, v224
	v_pk_add_f32 v[22:23], v[22:23], v[30:31]
	v_pk_add_f32 v[20:21], v[20:21], v[28:29]
	v_pk_add_f32 v[30:31], v[16:17], v[36:37]
	v_mul_f32_e32 v16, v21, v21
	v_mul_f32_e32 v17, v23, v23
	v_fmac_f32_e32 v16, v20, v20
	v_fmac_f32_e32 v17, v22, v22
	v_lshlrev_b32_e32 v38, 16, v225
	v_and_b32_e32 v39, 0xffff0000, v225
	v_add_f32_e32 v16, v16, v17
	v_mul_f32_e32 v17, v31, v31
	v_pk_add_f32 v[28:29], v[18:19], v[38:39]
	v_fmac_f32_e32 v17, v30, v30
	v_add_f32_e32 v16, v17, v16
	v_mul_f32_e32 v17, v29, v29
	v_fmac_f32_e32 v17, v28, v28
	v_add_f32_e32 v16, v17, v16
	v_add_f32_e32 v16, v40, v16
	ds_bpermute_b32 v17, v128, v16
	s_waitcnt lgkmcnt(1)
	v_lshl_add_u64 v[32:33], s[28:29], 0, v[100:101]
	v_lshl_add_u64 v[32:33], v[162:163], 1, v[32:33]
	v_cvt_pk_bf16_f32 v26, v26, v27
	v_cvt_pk_bf16_f32 v27, v34, v35
	s_waitcnt lgkmcnt(0)
	v_add_f32_e32 v16, v16, v17
	ds_bpermute_b32 v17, v129, v16
	global_store_dwordx4 v[32:33], v[24:27], off
	v_cvt_pk_bf16_f32 v18, v20, v21
	v_cvt_pk_bf16_f32 v19, v22, v23
	v_cvt_pk_bf16_f32 v20, v30, v31
	v_cvt_pk_bf16_f32 v21, v28, v29
	global_store_dwordx4 v[32:33], v[18:21], off offset:256
	s_and_saveexec_b64 s[38:39], s[6:7]
	s_cbranch_execz .LBB0_211
	s_waitcnt lgkmcnt(0)
	v_add_f32_e32 v18, v16, v17
	v_lshlrev_b64 v[16:17], 6, v[94:95]
	v_lshl_add_u64 v[16:17], s[30:31], 0, v[16:17]
	v_lshl_add_u64 v[16:17], s[64:65], 2, v[16:17]
	s_lshl_b32 s90, s61, 2
	v_lshl_add_u64 v[16:17], v[16:17], 0, s[90:91]
	global_store_dword v[16:17], v18, off
.LBB0_211:
	s_or_b64 exec, exec, s[38:39]
	s_waitcnt vmcnt(7)
	v_lshlrev_b32_e32 v18, 16, v226
	v_and_b32_e32 v19, 0xffff0000, v226
	v_lshlrev_b32_e32 v20, 16, v227
	v_and_b32_e32 v21, 0xffff0000, v227
	v_lshlrev_b32_e32 v22, 16, v228
	v_and_b32_e32 v23, 0xffff0000, v228
	v_lshlrev_b32_e32 v24, 16, v229
	v_and_b32_e32 v25, 0xffff0000, v229
	v_pk_add_f32 v[14:15], v[14:15], v[20:21]
	v_pk_add_f32 v[12:13], v[12:13], v[18:19]
	v_pk_add_f32 v[18:19], v[10:11], v[24:25]
	v_pk_add_f32 v[10:11], v[8:9], v[22:23]
	v_mul_f32_e32 v8, v13, v13
	v_mul_f32_e32 v9, v15, v15
	v_fmac_f32_e32 v8, v12, v12
	v_fmac_f32_e32 v9, v14, v14
	v_add_f32_e32 v8, v8, v9
	v_mul_f32_e32 v9, v11, v11
	v_fmac_f32_e32 v9, v10, v10
	v_add_f32_e32 v8, v9, v8
	v_mul_f32_e32 v9, v19, v19
	v_fmac_f32_e32 v9, v18, v18
	v_add_f32_e32 v24, v9, v8
	v_cvt_pk_bf16_f32 v8, v12, v13
	v_cvt_pk_bf16_f32 v9, v14, v15
	s_waitcnt vmcnt(6)
	v_lshlrev_b32_e32 v12, 16, v234
	v_and_b32_e32 v13, 0xffff0000, v234
	v_lshlrev_b32_e32 v14, 16, v235
	v_and_b32_e32 v15, 0xffff0000, v235
	v_lshlrev_b32_e32 v20, 16, v236
	v_and_b32_e32 v21, 0xffff0000, v236
	v_pk_add_f32 v[6:7], v[6:7], v[14:15]
	v_pk_add_f32 v[4:5], v[4:5], v[12:13]
	v_pk_add_f32 v[14:15], v[0:1], v[20:21]
	v_mul_f32_e32 v0, v5, v5
	v_mul_f32_e32 v1, v7, v7
	v_fmac_f32_e32 v0, v4, v4
	v_fmac_f32_e32 v1, v6, v6
	v_lshlrev_b32_e32 v22, 16, v237
	v_and_b32_e32 v23, 0xffff0000, v237
	v_add_f32_e32 v0, v0, v1
	v_mul_f32_e32 v1, v15, v15
	v_pk_add_f32 v[12:13], v[2:3], v[22:23]
	v_fmac_f32_e32 v1, v14, v14
	v_add_f32_e32 v0, v1, v0
	v_mul_f32_e32 v1, v13, v13
	v_fmac_f32_e32 v1, v12, v12
	v_add_f32_e32 v0, v1, v0
	v_add_f32_e32 v0, v24, v0
	ds_bpermute_b32 v1, v128, v0
	s_waitcnt lgkmcnt(1)
	v_lshl_add_u64 v[16:17], s[28:29], 0, v[96:97]
	v_lshl_add_u64 v[16:17], v[162:163], 1, v[16:17]
	v_cvt_pk_bf16_f32 v10, v10, v11
	v_cvt_pk_bf16_f32 v11, v18, v19
	s_waitcnt lgkmcnt(0)
	v_add_f32_e32 v0, v0, v1
	ds_bpermute_b32 v1, v129, v0
	global_store_dwordx4 v[16:17], v[8:11], off
	v_cvt_pk_bf16_f32 v2, v4, v5
	v_cvt_pk_bf16_f32 v3, v6, v7
	v_cvt_pk_bf16_f32 v4, v14, v15
	v_cvt_pk_bf16_f32 v5, v12, v13
	global_store_dwordx4 v[16:17], v[2:5], off offset:256
	s_and_saveexec_b64 s[38:39], s[6:7]
	s_cbranch_execz .LBB0_213
	s_waitcnt lgkmcnt(0)
	v_add_f32_e32 v2, v0, v1
	v_lshlrev_b64 v[0:1], 6, v[92:93]
	v_lshl_add_u64 v[0:1], s[30:31], 0, v[0:1]
	v_lshl_add_u64 v[0:1], s[64:65], 2, v[0:1]
	s_lshl_b32 s90, s61, 2
	v_lshl_add_u64 v[0:1], v[0:1], 0, s[90:91]
	global_store_dword v[0:1], v2, off

; __device__ __forceinline__ unsigned cvt_pk_bf16(float lo, float hi) { unsigned r; asm volatile("v_cvt_pk_bf16_f32 %0, %1, %2" : "=v"(r) : "v"(lo), "v"(hi)); return r; }
; #define GAS __attribute__((address_space(1)))
;     __device__ __forceinline__ void operator()(const f32x4 (&acc)[2][2][4][2], const Unit& u, int wr, int wc, int fr, int fq) const {
;     ...
;         for (int ai = 0; ai < 2; ++ai) {
;             u32x4 xo[4][2];
; #pragma unroll
;             for (int m = 0; m < 4; ++m)
; #pragma unroll
;                 for (int bj = 0; bj < 2; ++bj) xo[m][bj] = *(const GAS u32x4*)(xb + (size_t)(row0 + ai * 128 + m * 16) * DM + col0 + bj * 128);
;             asm volatile("" ::: "memory");
; #pragma unroll
;             for (int m = 0; m < 4; ++m) {
;                 const int row = row0 + ai * 128 + m * 16; float part = 0.f;
; #pragma unroll
;                 for (int bj = 0; bj < 2; ++bj) {
;                     bf16_t* xp = xb + (size_t)row * DM + col0 + bj * 128;
;                     const u32x4 q = xo[m][bj];
;                     f32x4 x0, x1;
;                     x0[0] = __uint_as_float(q.x << 16); x0[1] = __uint_as_float(q.x & 0xffff0000u); x0[2] = __uint_as_float(q.y << 16); x0[3] = __uint_as_float(q.y & 0xffff0000u);
;                     x1[0] = __uint_as_float(q.z << 16); x1[1] = __uint_as_float(q.z & 0xffff0000u); x1[2] = __uint_as_float(q.w << 16); x1[3] = __uint_as_float(q.w & 0xffff0000u);
;                     x0 = x0 + acc[ai][bj][m][0]; x1 = x1 + acc[ai][bj][m][1];
;                     part += (x0[0] * x0[0] + x0[1] * x0[1]) + (x0[2] * x0[2] + x0[3] * x0[3]) + (x1[0] * x1[0] + x1[1] * x1[1]) + (x1[2] * x1[2] + x1[3] * x1[3]);
;                     u32x4 w; w.x = cvt_pk_bf16(x0[0], x0[1]); w.y = cvt_pk_bf16(x0[2], x0[3]); w.z = cvt_pk_bf16(x1[0], x1[1]); w.w = cvt_pk_bf16(x1[2], x1[3]);
;                     *(GAS u32x4*)xp = w;
;                 }
;                 part += __shfl_xor(part, 16); part += __shfl_xor(part, 32);
;                 if (fq == 0) *(GAS float*)(ssacc + (size_t)row * 16 + u.pn * 4 + wc) = part;
;             }
.LBB0_297:
	v_lshl_or_b32 v162, s87, 8, v182
	v_lshl_add_u32 v166, s40, 8, v180
	v_ashrrev_i32_e32 v163, 31, v162
	v_lshlrev_b64 v[192:193], 1, v[162:163]
	v_ashrrev_i32_e32 v167, 31, v166
	v_lshl_add_u64 v[164:165], s[24:25], 0, v[192:193]
	v_lshlrev_b64 v[194:195], 11, v[166:167]
	v_lshl_add_u64 v[112:113], v[164:165], 0, v[194:195]
	global_load_dwordx4 v[184:187], v[112:113], off
	global_load_dwordx4 v[188:191], v[112:113], off offset:256
	v_or_b32_e32 v174, 16, v166
	v_ashrrev_i32_e32 v175, 31, v174
	v_or_b32_e32 v170, 32, v166
	v_lshlrev_b64 v[178:179], 11, v[174:175]
	v_ashrrev_i32_e32 v171, 31, v170
	v_or_b32_e32 v168, 48, v166
	v_lshl_add_u64 v[112:113], v[164:165], 0, v[178:179]
	v_lshlrev_b64 v[176:177], 11, v[170:171]
	v_ashrrev_i32_e32 v169, 31, v168
	global_load_dwordx4 v[148:151], v[112:113], off
	global_load_dwordx4 v[136:139], v[112:113], off offset:256
	v_lshl_add_u64 v[112:113], v[164:165], 0, v[176:177]
	v_lshlrev_b64 v[172:173], 11, v[168:169]
	global_load_dwordx4 v[124:127], v[112:113], off
	global_load_dwordx4 v[120:123], v[112:113], off offset:256
	v_lshl_add_u64 v[112:113], v[164:165], 0, v[172:173]
	global_load_dwordx4 v[116:119], v[112:113], off
	s_nop 0
	global_load_dwordx4 v[112:115], v[112:113], off offset:256
	v_mov_b32_e32 v243, 0
	v_add_u32_e32 v242, 0x80, v166
	v_lshlrev_b32_e32 v242, 11, v242
	v_lshl_add_u64 v[240:241], v[164:165], 0, v[242:243]
	global_load_dwordx4 v[198:201], v[240:241], off
	global_load_dwordx4 v[202:205], v[240:241], off offset:256
	v_add_u32_e32 v242, 0x90, v166
	v_lshlrev_b32_e32 v242, 11, v242
	v_lshl_add_u64 v[240:241], v[164:165], 0, v[242:243]
	global_load_dwordx4 v[206:209], v[240:241], off
	global_load_dwordx4 v[210:213], v[240:241], off offset:256
	v_add_u32_e32 v242, 0xa0, v166
	v_lshlrev_b32_e32 v242, 11, v242
	v_lshl_add_u64 v[240:241], v[164:165], 0, v[242:243]
	global_load_dwordx4 v[214:217], v[240:241], off
	global_load_dwordx4 v[222:225], v[240:241], off offset:256
	v_add_u32_e32 v242, 0xb0, v166
	v_lshlrev_b32_e32 v242, 11, v242
	v_lshl_add_u64 v[240:241], v[164:165], 0, v[242:243]
	global_load_dwordx4 v[226:229], v[240:241], off
	global_load_dwordx4 v[234:237], v[240:241], off offset:256
	v_lshl_add_u64 v[194:195], s[24:25], 0, v[194:195]
	v_lshl_add_u64 v[192:193], v[194:195], 0, v[192:193]
	s_lshl_b32 s34, s87, 2
	s_ashr_i32 s35, s34, 31
	s_waitcnt vmcnt(8)
	v_lshlrev_b32_e32 v194, 16, v184
	v_and_b32_e32 v195, 0xffff0000, v184
	v_lshlrev_b32_e32 v184, 16, v185
	v_and_b32_e32 v185, 0xffff0000, v185
	v_lshlrev_b32_e32 v196, 16, v186
	v_and_b32_e32 v197, 0xffff0000, v186
	v_lshlrev_b32_e32 v186, 16, v187
	v_and_b32_e32 v187, 0xffff0000, v187
	v_pk_add_f32 v[146:147], v[146:147], v[184:185]
	v_pk_add_f32 v[144:145], v[144:145], v[194:195]
	v_pk_add_f32 v[184:185], v[142:143], v[186:187]
	v_pk_add_f32 v[142:143], v[140:141], v[196:197]
	v_mul_f32_e32 v140, v145, v145
	v_mul_f32_e32 v141, v147, v147
	v_fmac_f32_e32 v140, v144, v144
	v_fmac_f32_e32 v141, v146, v146
	v_add_f32_e32 v140, v140, v141
	v_mul_f32_e32 v141, v143, v143
	v_fmac_f32_e32 v141, v142, v142
	v_add_f32_e32 v140, v141, v140
	v_mul_f32_e32 v141, v185, v185
	v_fmac_f32_e32 v141, v184, v184
	v_add_f32_e32 v186, v141, v140
	v_cvt_pk_bf16_f32 v140, v144, v145
	v_cvt_pk_bf16_f32 v141, v146, v147
	v_cvt_pk_bf16_f32 v142, v142, v143
	v_cvt_pk_bf16_f32 v143, v184, v185
	global_store_dwordx4 v[192:193], v[140:143], off
	v_lshlrev_b32_e32 v144, 16, v190
	v_and_b32_e32 v145, 0xffff0000, v190
	v_lshlrev_b32_e32 v140, 16, v188
	v_and_b32_e32 v141, 0xffff0000, v188
	v_lshlrev_b32_e32 v142, 16, v189
	v_and_b32_e32 v143, 0xffff0000, v189
	v_lshlrev_b32_e32 v146, 16, v191
	v_and_b32_e32 v147, 0xffff0000, v191
	v_pk_add_f32 v[134:135], v[134:135], v[142:143]
	v_pk_add_f32 v[132:133], v[132:133], v[140:141]
	v_pk_add_f32 v[140:141], v[130:131], v[146:147]
	v_pk_add_f32 v[130:131], v[128:129], v[144:145]
	v_mul_f32_e32 v128, v133, v133
	v_mul_f32_e32 v129, v135, v135
	v_fmac_f32_e32 v128, v132, v132
	v_fmac_f32_e32 v129, v134, v134
	v_add_f32_e32 v128, v128, v129
	v_mul_f32_e32 v129, v131, v131
	v_fmac_f32_e32 v129, v130, v130
	v_add_f32_e32 v128, v129, v128
	v_mul_f32_e32 v129, v141, v141
	v_fmac_f32_e32 v129, v140, v140
	v_add_f32_e32 v128, v129, v128
	v_add_f32_e32 v142, v186, v128
	v_cvt_pk_bf16_f32 v128, v132, v133
	v_cvt_pk_bf16_f32 v129, v134, v135
	v_cvt_pk_bf16_f32 v130, v130, v131
	v_cvt_pk_bf16_f32 v131, v140, v141
	global_store_dwordx4 v[192:193], v[128:131], off offset:256
	s_nop 1
	v_and_b32_e32 v129, 64, v244
	v_xor_b32_e32 v128, 16, v244
	v_add_u32_e32 v129, 64, v129
	v_cmp_lt_i32_e32 vcc, v128, v129
	v_xor_b32_e32 v131, 32, v244
	s_nop 0
	v_cndmask_b32_e32 v128, v244, v128, vcc
	v_lshlrev_b32_e32 v128, 2, v128
	ds_bpermute_b32 v130, v128, v142
	v_cmp_lt_i32_e32 vcc, v131, v129
	s_waitcnt lgkmcnt(0)
	v_add_f32_e32 v130, v142, v130
	v_cndmask_b32_e32 v129, v244, v131, vcc
	v_lshlrev_b32_e32 v129, 2, v129
	ds_bpermute_b32 v131, v129, v130
	s_and_saveexec_b64 s[36:37], s[6:7]
	s_cbranch_execz .LBB0_299
	s_waitcnt lgkmcnt(0)
	v_add_f32_e32 v132, v130, v131
	v_lshlrev_b64 v[130:131], 6, v[166:167]
	v_lshl_add_u64 v[130:131], s[26:27], 0, v[130:131]
	v_lshl_add_u64 v[130:131], s[34:35], 2, v[130:131]
	s_lshl_b32 s90, s61, 2
	v_lshl_add_u64 v[130:131], v[130:131], 0, s[90:91]
	global_store_dword v[130:131], v132, off

; __device__ __forceinline__ unsigned cvt_pk_bf16(float lo, float hi) { unsigned r; asm volatile("v_cvt_pk_bf16_f32 %0, %1, %2" : "=v"(r) : "v"(lo), "v"(hi)); return r; }
; #define GAS __attribute__((address_space(1)))
;     __device__ __forceinline__ void operator()(const f32x4 (&acc)[2][2][4][2], const Unit& u, int wr, int wc, int fr, int fq) const {
;     ...
;         for (int ai = 0; ai < 2; ++ai) {
;             u32x4 xo[4][2];
; #pragma unroll
;             for (int m = 0; m < 4; ++m)
; #pragma unroll
;                 for (int bj = 0; bj < 2; ++bj) xo[m][bj] = *(const GAS u32x4*)(xb + (size_t)(row0 + ai * 128 + m * 16) * DM + col0 + bj * 128);
;             asm volatile("" ::: "memory");
; #pragma unroll
;             for (int m = 0; m < 4; ++m) {
;                 const int row = row0 + ai * 128 + m * 16; float part = 0.f;
; #pragma unroll
;                 for (int bj = 0; bj < 2; ++bj) {
;                     bf16_t* xp = xb + (size_t)row * DM + col0 + bj * 128;
;                     const u32x4 q = xo[m][bj];
;                     f32x4 x0, x1;
;                     x0[0] = __uint_as_float(q.x << 16); x0[1] = __uint_as_float(q.x & 0xffff0000u); x0[2] = __uint_as_float(q.y << 16); x0[3] = __uint_as_float(q.y & 0xffff0000u);
;                     x1[0] = __uint_as_float(q.z << 16); x1[1] = __uint_as_float(q.z & 0xffff0000u); x1[2] = __uint_as_float(q.w << 16); x1[3] = __uint_as_float(q.w & 0xffff0000u);
;                     x0 = x0 + acc[ai][bj][m][0]; x1 = x1 + acc[ai][bj][m][1];
;                     part += (x0[0] * x0[0] + x0[1] * x0[1]) + (x0[2] * x0[2] + x0[3] * x0[3]) + (x1[0] * x1[0] + x1[1] * x1[1]) + (x1[2] * x1[2] + x1[3] * x1[3]);
;                     u32x4 w; w.x = cvt_pk_bf16(x0[0], x0[1]); w.y = cvt_pk_bf16(x0[2], x0[3]); w.z = cvt_pk_bf16(x1[0], x1[1]); w.w = cvt_pk_bf16(x1[2], x1[3]);
;                     *(GAS u32x4*)xp = w;
;                 }
;                 part += __shfl_xor(part, 16); part += __shfl_xor(part, 32);
;                 if (fq == 0) *(GAS float*)(ssacc + (size_t)row * 16 + u.pn * 4 + wc) = part;
;             }
.LBB0_305:
	s_or_b64 exec, exec, s[36:37]
	v_add_u32_e32 v104, 0x80, v166
	v_ashrrev_i32_e32 v105, 31, v104
	v_lshlrev_b64 v[106:107], 11, v[104:105]
	s_waitcnt lgkmcnt(0)
	v_lshl_add_u64 v[64:65], v[164:165], 0, v[106:107]
	v_add_u32_e32 v98, 0x90, v166
	v_ashrrev_i32_e32 v99, 31, v98
	v_add_u32_e32 v94, 0xa0, v166
	v_lshlrev_b64 v[102:103], 11, v[98:99]
	v_ashrrev_i32_e32 v95, 31, v94
	v_add_u32_e32 v92, 0xb0, v166
	v_lshl_add_u64 v[64:65], v[164:165], 0, v[102:103]
	v_lshlrev_b64 v[100:101], 11, v[94:95]
	v_ashrrev_i32_e32 v93, 31, v92
	v_lshl_add_u64 v[64:65], v[164:165], 0, v[100:101]
	v_lshlrev_b64 v[96:97], 11, v[92:93]
	v_lshl_add_u64 v[64:65], v[164:165], 0, v[96:97]
	s_nop 0
	v_lshl_add_u64 v[106:107], s[24:25], 0, v[106:107]
	v_lshl_add_u64 v[106:107], v[162:163], 1, v[106:107]
	s_waitcnt vmcnt(8)
	v_lshlrev_b32_e32 v112, 16, v198
	v_and_b32_e32 v113, 0xffff0000, v198
	v_lshlrev_b32_e32 v108, 16, v199
	v_and_b32_e32 v109, 0xffff0000, v199
	v_lshlrev_b32_e32 v114, 16, v200
	v_and_b32_e32 v115, 0xffff0000, v200
	v_lshlrev_b32_e32 v110, 16, v201
	v_and_b32_e32 v111, 0xffff0000, v201
	v_pk_add_f32 v[62:63], v[62:63], v[108:109]
	v_pk_add_f32 v[60:61], v[60:61], v[112:113]
	v_pk_add_f32 v[108:109], v[58:59], v[110:111]
	v_pk_add_f32 v[58:59], v[56:57], v[114:115]
	v_mul_f32_e32 v56, v61, v61
	v_mul_f32_e32 v57, v63, v63
	v_fmac_f32_e32 v56, v60, v60
	v_fmac_f32_e32 v57, v62, v62
	v_add_f32_e32 v56, v56, v57
	v_mul_f32_e32 v57, v59, v59
	v_fmac_f32_e32 v57, v58, v58
	v_add_f32_e32 v56, v57, v56
	v_mul_f32_e32 v57, v109, v109
	v_fmac_f32_e32 v57, v108, v108
	v_add_f32_e32 v110, v57, v56
	v_cvt_pk_bf16_f32 v56, v60, v61
	v_cvt_pk_bf16_f32 v57, v62, v63
	v_cvt_pk_bf16_f32 v58, v58, v59
	v_cvt_pk_bf16_f32 v59, v108, v109
	global_store_dwordx4 v[106:107], v[56:59], off
	s_waitcnt vmcnt(7)
	v_lshlrev_b32_e32 v60, 16, v204
	v_and_b32_e32 v61, 0xffff0000, v204
	v_lshlrev_b32_e32 v56, 16, v202
	v_and_b32_e32 v57, 0xffff0000, v202
	v_lshlrev_b32_e32 v58, 16, v203
	v_and_b32_e32 v59, 0xffff0000, v203
	v_lshlrev_b32_e32 v62, 16, v205
	v_and_b32_e32 v63, 0xffff0000, v205
	v_pk_add_f32 v[54:55], v[54:55], v[58:59]
	v_pk_add_f32 v[52:53], v[52:53], v[56:57]
	v_pk_add_f32 v[56:57], v[50:51], v[62:63]
	v_pk_add_f32 v[50:51], v[48:49], v[60:61]
	v_mul_f32_e32 v48, v53, v53
	v_mul_f32_e32 v49, v55, v55
	v_fmac_f32_e32 v48, v52, v52
	v_fmac_f32_e32 v49, v54, v54
	v_add_f32_e32 v48, v48, v49
	v_mul_f32_e32 v49, v51, v51
	v_fmac_f32_e32 v49, v50, v50
	v_add_f32_e32 v48, v49, v48
	v_mul_f32_e32 v49, v57, v57
	v_fmac_f32_e32 v49, v56, v56
	v_add_f32_e32 v48, v49, v48
	v_add_f32_e32 v58, v110, v48
	v_cvt_pk_bf16_f32 v48, v52, v53
	v_cvt_pk_bf16_f32 v49, v54, v55
	v_cvt_pk_bf16_f32 v50, v50, v51
	v_cvt_pk_bf16_f32 v51, v56, v57
	global_store_dwordx4 v[106:107], v[48:51], off offset:256
	ds_bpermute_b32 v48, v128, v58
	s_waitcnt lgkmcnt(0)
	v_add_f32_e32 v48, v58, v48
	ds_bpermute_b32 v49, v129, v48
	s_and_saveexec_b64 s[36:37], s[6:7]
	s_cbranch_execz .LBB0_307
	s_waitcnt lgkmcnt(0)
	v_add_f32_e32 v50, v48, v49
	v_lshlrev_b64 v[48:49], 6, v[104:105]
	v_lshl_add_u64 v[48:49], s[26:27], 0, v[48:49]
	v_lshl_add_u64 v[48:49], s[34:35], 2, v[48:49]
	s_lshl_b32 s90, s61, 2
	v_lshl_add_u64 v[48:49], v[48:49], 0, s[90:91]
	global_store_dword v[48:49], v50, off
.LBB0_307:
	s_or_b64 exec, exec, s[36:37]
	s_waitcnt vmcnt(7)
	v_lshlrev_b32_e32 v50, 16, v206
	v_and_b32_e32 v51, 0xffff0000, v206
	v_lshlrev_b32_e32 v52, 16, v207
	v_and_b32_e32 v53, 0xffff0000, v207
	v_lshlrev_b32_e32 v54, 16, v208
	v_and_b32_e32 v55, 0xffff0000, v208
	v_lshlrev_b32_e32 v56, 16, v209
	v_and_b32_e32 v57, 0xffff0000, v209
	v_pk_add_f32 v[46:47], v[46:47], v[52:53]
	v_pk_add_f32 v[44:45], v[44:45], v[50:51]
	v_pk_add_f32 v[50:51], v[42:43], v[56:57]
	v_pk_add_f32 v[42:43], v[40:41], v[54:55]
	v_mul_f32_e32 v40, v45, v45
	v_mul_f32_e32 v41, v47, v47
	v_fmac_f32_e32 v40, v44, v44
	v_fmac_f32_e32 v41, v46, v46
	v_add_f32_e32 v40, v40, v41
	v_mul_f32_e32 v41, v43, v43
	v_fmac_f32_e32 v41, v42, v42
	v_add_f32_e32 v40, v41, v40
	v_mul_f32_e32 v41, v51, v51
	v_fmac_f32_e32 v41, v50, v50
	v_add_f32_e32 v56, v41, v40
	v_cvt_pk_bf16_f32 v40, v44, v45
	v_cvt_pk_bf16_f32 v41, v46, v47
	s_waitcnt vmcnt(6)
	v_lshlrev_b32_e32 v44, 16, v210
	v_and_b32_e32 v45, 0xffff0000, v210
	v_lshlrev_b32_e32 v46, 16, v211
	v_and_b32_e32 v47, 0xffff0000, v211
	v_lshlrev_b32_e32 v52, 16, v212
	v_and_b32_e32 v53, 0xffff0000, v212
	v_pk_add_f32 v[38:39], v[38:39], v[46:47]
	v_pk_add_f32 v[36:37], v[36:37], v[44:45]
	v_pk_add_f32 v[46:47], v[32:33], v[52:53]
	v_mul_f32_e32 v32, v37, v37
	v_mul_f32_e32 v33, v39, v39
	v_fmac_f32_e32 v32, v36, v36
	v_fmac_f32_e32 v33, v38, v38
	v_lshlrev_b32_e32 v54, 16, v213
	v_and_b32_e32 v55, 0xffff0000, v213
	v_add_f32_e32 v32, v32, v33
	v_mul_f32_e32 v33, v47, v47
	v_pk_add_f32 v[44:45], v[34:35], v[54:55]
	v_fmac_f32_e32 v33, v46, v46
	v_add_f32_e32 v32, v33, v32
	v_mul_f32_e32 v33, v45, v45
	v_fmac_f32_e32 v33, v44, v44
	v_add_f32_e32 v32, v33, v32
	v_add_f32_e32 v32, v56, v32
	ds_bpermute_b32 v33, v128, v32
	s_waitcnt lgkmcnt(1)
	v_lshl_add_u64 v[48:49], s[24:25], 0, v[102:103]
	v_lshl_add_u64 v[48:49], v[162:163], 1, v[48:49]
	v_cvt_pk_bf16_f32 v42, v42, v43
	v_cvt_pk_bf16_f32 v43, v50, v51
	s_waitcnt lgkmcnt(0)
	v_add_f32_e32 v32, v32, v33
	ds_bpermute_b32 v33, v129, v32
	global_store_dwordx4 v[48:49], v[40:43], off
	v_cvt_pk_bf16_f32 v34, v36, v37
	v_cvt_pk_bf16_f32 v35, v38, v39
	v_cvt_pk_bf16_f32 v36, v46, v47
	v_cvt_pk_bf16_f32 v37, v44, v45
	global_store_dwordx4 v[48:49], v[34:37], off offset:256
	s_and_saveexec_b64 s[36:37], s[6:7]
	s_cbranch_execz .LBB0_309
	s_waitcnt lgkmcnt(0)
	v_add_f32_e32 v34, v32, v33
	v_lshlrev_b64 v[32:33], 6, v[98:99]
	v_lshl_add_u64 v[32:33], s[26:27], 0, v[32:33]
	v_lshl_add_u64 v[32:33], s[34:35], 2, v[32:33]
	s_lshl_b32 s90, s61, 2
	v_lshl_add_u64 v[32:33], v[32:33], 0, s[90:91]
	global_store_dword v[32:33], v34, off
; __device__ __forceinline__ unsigned cvt_pk_bf16(float lo, float hi) { unsigned r; asm volatile("v_cvt_pk_bf16_f32 %0, %1, %2" : "=v"(r) : "v"(lo), "v"(hi)); return r; }
; #define GAS __attribute__((address_space(1)))
;     __device__ __forceinline__ void operator()(const f32x4 (&acc)[2][2][4][2], const Unit& u, int wr, int wc, int fr, int fq) const {
;     ...
;             for (int m = 0; m < 4; ++m) {
;                 const int row = row0 + ai * 128 + m * 16; float part = 0.f;
; #pragma unroll
;                 for (int bj = 0; bj < 2; ++bj) {
;                     bf16_t* xp = xb + (size_t)row * DM + col0 + bj * 128;
;                     const u32x4 q = xo[m][bj];
;                     f32x4 x0, x1;
;                     x0[0] = __uint_as_float(q.x << 16); x0[1] = __uint_as_float(q.x & 0xffff0000u); x0[2] = __uint_as_float(q.y << 16); x0[3] = __uint_as_float(q.y & 0xffff0000u);
;                     x1[0] = __uint_as_float(q.z << 16); x1[1] = __uint_as_float(q.z & 0xffff0000u); x1[2] = __uint_as_float(q.w << 16); x1[3] = __uint_as_float(q.w & 0xffff0000u);
;                     x0 = x0 + acc[ai][bj][m][0]; x1 = x1 + acc[ai][bj][m][1];
;                     part += (x0[0] * x0[0] + x0[1] * x0[1]) + (x0[2] * x0[2] + x0[3] * x0[3]) + (x1[0] * x1[0] + x1[1] * x1[1]) + (x1[2] * x1[2] + x1[3] * x1[3]);
;                     u32x4 w; w.x = cvt_pk_bf16(x0[0], x0[1]); w.y = cvt_pk_bf16(x0[2], x0[3]); w.z = cvt_pk_bf16(x1[0], x1[1]); w.w = cvt_pk_bf16(x1[2], x1[3]);
;                     *(GAS u32x4*)xp = w;
;                 }
;                 part += __shfl_xor(part, 16); part += __shfl_xor(part, 32);
;                 if (fq == 0) *(GAS float*)(ssacc + (size_t)row * 16 + u.pn * 4 + wc) = part;
;             }
.LBB0_309:
	s_or_b64 exec, exec, s[36:37]
	s_waitcnt vmcnt(7)
	v_lshlrev_b32_e32 v34, 16, v214
	v_and_b32_e32 v35, 0xffff0000, v214
	v_lshlrev_b32_e32 v36, 16, v215
	v_and_b32_e32 v37, 0xffff0000, v215
	v_lshlrev_b32_e32 v38, 16, v216
	v_and_b32_e32 v39, 0xffff0000, v216
	v_lshlrev_b32_e32 v40, 16, v217
	v_and_b32_e32 v41, 0xffff0000, v217
	v_pk_add_f32 v[30:31], v[30:31], v[36:37]
	v_pk_add_f32 v[28:29], v[28:29], v[34:35]
	v_pk_add_f32 v[34:35], v[26:27], v[40:41]
	v_pk_add_f32 v[26:27], v[24:25], v[38:39]
	v_mul_f32_e32 v24, v29, v29
	v_mul_f32_e32 v25, v31, v31
	v_fmac_f32_e32 v24, v28, v28
	v_fmac_f32_e32 v25, v30, v30
	v_add_f32_e32 v24, v24, v25
	v_mul_f32_e32 v25, v27, v27
	v_fmac_f32_e32 v25, v26, v26
	v_add_f32_e32 v24, v25, v24
	v_mul_f32_e32 v25, v35, v35
	v_fmac_f32_e32 v25, v34, v34
	v_add_f32_e32 v40, v25, v24
	v_cvt_pk_bf16_f32 v24, v28, v29
	v_cvt_pk_bf16_f32 v25, v30, v31
	s_waitcnt vmcnt(6)
	v_lshlrev_b32_e32 v28, 16, v222
	v_and_b32_e32 v29, 0xffff0000, v222
	v_lshlrev_b32_e32 v30, 16, v223
	v_and_b32_e32 v31, 0xffff0000, v223
	v_lshlrev_b32_e32 v36, 16, v224
	v_and_b32_e32 v37, 0xffff0000, v224
	v_pk_add_f32 v[22:23], v[22:23], v[30:31]
	v_pk_add_f32 v[20:21], v[20:21], v[28:29]
	v_pk_add_f32 v[30:31], v[16:17], v[36:37]
	v_mul_f32_e32 v16, v21, v21
	v_mul_f32_e32 v17, v23, v23
	v_fmac_f32_e32 v16, v20, v20
	v_fmac_f32_e32 v17, v22, v22
	v_lshlrev_b32_e32 v38, 16, v225
	v_and_b32_e32 v39, 0xffff0000, v225
	v_add_f32_e32 v16, v16, v17
	v_mul_f32_e32 v17, v31, v31
	v_pk_add_f32 v[28:29], v[18:19], v[38:39]
	v_fmac_f32_e32 v17, v30, v30
	v_add_f32_e32 v16, v17, v16
	v_mul_f32_e32 v17, v29, v29
	v_fmac_f32_e32 v17, v28, v28
	v_add_f32_e32 v16, v17, v16
	v_add_f32_e32 v16, v40, v16
	ds_bpermute_b32 v17, v128, v16
	s_waitcnt lgkmcnt(1)
	v_lshl_add_u64 v[32:33], s[24:25], 0, v[100:101]
	v_lshl_add_u64 v[32:33], v[162:163], 1, v[32:33]
	v_cvt_pk_bf16_f32 v26, v26, v27
	v_cvt_pk_bf16_f32 v27, v34, v35
	s_waitcnt lgkmcnt(0)
	v_add_f32_e32 v16, v16, v17
	ds_bpermute_b32 v17, v129, v16
	global_store_dwordx4 v[32:33], v[24:27], off
	v_cvt_pk_bf16_f32 v18, v20, v21
	v_cvt_pk_bf16_f32 v19, v22, v23
	v_cvt_pk_bf16_f32 v20, v30, v31
	v_cvt_pk_bf16_f32 v21, v28, v29
	global_store_dwordx4 v[32:33], v[18:21], off offset:256
	s_and_saveexec_b64 s[36:37], s[6:7]
	s_cbranch_execz .LBB0_311
	s_waitcnt lgkmcnt(0)
	v_add_f32_e32 v18, v16, v17
	v_lshlrev_b64 v[16:17], 6, v[94:95]
	v_lshl_add_u64 v[16:17], s[26:27], 0, v[16:17]
	v_lshl_add_u64 v[16:17], s[34:35], 2, v[16:17]
	s_lshl_b32 s90, s61, 2
	v_lshl_add_u64 v[16:17], v[16:17], 0, s[90:91]
	global_store_dword v[16:17], v18, off
.LBB0_311:
	s_or_b64 exec, exec, s[36:37]
	s_waitcnt vmcnt(7)
	v_lshlrev_b32_e32 v18, 16, v226
	v_and_b32_e32 v19, 0xffff0000, v226
	v_lshlrev_b32_e32 v20, 16, v227
	v_and_b32_e32 v21, 0xffff0000, v227
	v_lshlrev_b32_e32 v22, 16, v228
	v_and_b32_e32 v23, 0xffff0000, v228
	v_lshlrev_b32_e32 v24, 16, v229
	v_and_b32_e32 v25, 0xffff0000, v229
	v_pk_add_f32 v[14:15], v[14:15], v[20:21]
	v_pk_add_f32 v[12:13], v[12:13], v[18:19]
	v_pk_add_f32 v[18:19], v[10:11], v[24:25]
	v_pk_add_f32 v[10:11], v[8:9], v[22:23]
	v_mul_f32_e32 v8, v13, v13
	v_mul_f32_e32 v9, v15, v15
	v_fmac_f32_e32 v8, v12, v12
	v_fmac_f32_e32 v9, v14, v14
	v_add_f32_e32 v8, v8, v9
	v_mul_f32_e32 v9, v11, v11
	v_fmac_f32_e32 v9, v10, v10
	v_add_f32_e32 v8, v9, v8
	v_mul_f32_e32 v9, v19, v19
	v_fmac_f32_e32 v9, v18, v18
	v_add_f32_e32 v24, v9, v8
	v_cvt_pk_bf16_f32 v8, v12, v13
	v_cvt_pk_bf16_f32 v9, v14, v15
	s_waitcnt vmcnt(6)
	v_lshlrev_b32_e32 v12, 16, v234
	v_and_b32_e32 v13, 0xffff0000, v234
	v_lshlrev_b32_e32 v14, 16, v235
	v_and_b32_e32 v15, 0xffff0000, v235
	v_lshlrev_b32_e32 v20, 16, v236
	v_and_b32_e32 v21, 0xffff0000, v236
	v_pk_add_f32 v[6:7], v[6:7], v[14:15]
	v_pk_add_f32 v[4:5], v[4:5], v[12:13]
	v_pk_add_f32 v[14:15], v[0:1], v[20:21]
	v_mul_f32_e32 v0, v5, v5
	v_mul_f32_e32 v1, v7, v7
	v_fmac_f32_e32 v0, v4, v4
	v_fmac_f32_e32 v1, v6, v6
	v_lshlrev_b32_e32 v22, 16, v237
	v_and_b32_e32 v23, 0xffff0000, v237
	v_add_f32_e32 v0, v0, v1
	v_mul_f32_e32 v1, v15, v15
	v_pk_add_f32 v[12:13], v[2:3], v[22:23]
	v_fmac_f32_e32 v1, v14, v14
	v_add_f32_e32 v0, v1, v0
	v_mul_f32_e32 v1, v13, v13
	v_fmac_f32_e32 v1, v12, v12
	v_add_f32_e32 v0, v1, v0
	v_add_f32_e32 v0, v24, v0
	ds_bpermute_b32 v1, v128, v0
	s_waitcnt lgkmcnt(1)
	v_lshl_add_u64 v[16:17], s[24:25], 0, v[96:97]
	v_lshl_add_u64 v[16:17], v[162:163], 1, v[16:17]
	v_cvt_pk_bf16_f32 v10, v10, v11
	v_cvt_pk_bf16_f32 v11, v18, v19
	s_waitcnt lgkmcnt(0)
	v_add_f32_e32 v0, v0, v1
	ds_bpermute_b32 v1, v129, v0
	global_store_dwordx4 v[16:17], v[8:11], off
	v_cvt_pk_bf16_f32 v2, v4, v5
	v_cvt_pk_bf16_f32 v3, v6, v7
	v_cvt_pk_bf16_f32 v4, v14, v15
	v_cvt_pk_bf16_f32 v5, v12, v13
	global_store_dwordx4 v[16:17], v[2:5], off offset:256
	s_and_saveexec_b64 s[36:37], s[6:7]
	s_cbranch_execz .LBB0_313
	s_waitcnt lgkmcnt(0)
	v_add_f32_e32 v2, v0, v1
	v_lshlrev_b64 v[0:1], 6, v[92:93]
	v_lshl_add_u64 v[0:1], s[26:27], 0, v[0:1]
	v_lshl_add_u64 v[0:1], s[34:35], 2, v[0:1]
	s_lshl_b32 s90, s61, 2
	v_lshl_add_u64 v[0:1], v[0:1], 0, s[90:91]
	global_store_dword v[0:1], v2, off

; #define LAS __attribute__((address_space(3)))
; #define GAS __attribute__((address_space(1)))
; __device__ __forceinline__ void attn_unit(LAS unsigned char* lds, bf16_t* Qm, const bf16_t* __restrict__ Kb, const bf16_t* __restrict__ Vt,
;                                           int b, int h, int qb, int lgS, float lam, float oscale, const float* __restrict__ subg, float* stash) {
;     ...
;         const bf16_t* qp = Qm + (size_t)(tok0 + r32) * MIXW + (2 * h + c) * 64 + hi * 8;
;         bf16x8 qf[4];
; #pragma unroll
;         for (int d0 = 0; d0 < 4; ++d0) qf[d0] = *(const GAS bf16x8*)(qp + d0 * 16);
; #pragma unroll
;         for (int i = 0; i < 4; ++i)
; #pragma unroll
;             for (int r = 0; r < 16; ++r) o[i][r] = 0.f;
;         float mhat, lrun;
;         f32x16 negm;
; #pragma unroll
;         for (int r = 0; r < 16; ++r) negm[r] = 0.f;
;         const bf16_t* kg = Kb + (size_t)((b << lgS) + (tid >> 3)) * 512 + (2 * h + c) * 64 + (tid & 7) * 8;
;         const bf16_t* vg0 = Vt + ((size_t)(b * 512 + h * 128 + (tid >> 3)) << lgS) + (tid & 7) * 8;
;         const bf16_t* vg1 = vg0 + ((size_t)64 << lgS);
;         u32x4 kreg, vreg0, vreg1;
;         {
;             kreg = *(const GAS u32x4*)kg; vreg0 = *(const GAS u32x4*)vg0; vreg1 = *(const GAS u32x4*)vg1;
;             const u32x4 k1 = *(const GAS u32x4*)(kg + (size_t)64 * 512), k2 = *(const GAS u32x4*)(kg + (size_t)2 * 64 * 512), v10 = *(const GAS u32x4*)(vg0 + 64), v11 = *(const GAS u32x4*)(vg1 + 64);
;             *(LAS u32x4*)(lds + kw) = kreg; *(LAS u32x4*)(lds + vw0) = vreg0; *(LAS u32x4*)(lds + vw1) = vreg1;
;             *(LAS u32x4*)(lds + KBUF + kw) = k1; *(LAS u32x4*)(lds + VBUF + vw0) = v10; *(LAS u32x4*)(lds + VBUF + vw1) = v11;
;             *(LAS u32x4*)(lds + 2 * KBUF + kw) = k2;
;             kreg = *(const GAS u32x4*)(kg + (size_t)3 * 64 * 512); vreg0 = *(const GAS u32x4*)(vg0 + 2 * 64); vreg1 = *(const GAS u32x4*)(vg1 + 2 * 64);
.LBB0_349:
	s_and_b64 vcc, exec, s[26:27]
	s_cbranch_vccz .Lmy_skip_pf
	s_mov_b32 m0, 0x18000
	s_lshl_b32 s100, s5, 1
	s_add_u32 s100, s100, 0x80
	s_mov_b32 s101, 0
	v_lshl_add_u64 v[84:85], v[226:227], 0, s[100:101]
	global_load_lds_dword v[84:85], off
	s_lshl_b32 s100, s5, 1
	s_add_u32 s100, s100, 0x80
	v_lshl_add_u64 v[86:87], v[228:229], 0, s[100:101]
	global_load_lds_dword v[86:87], off
	s_add_u32 s100, s100, 0x10000
	v_lshl_add_u64 v[88:89], v[228:229], 0, s[100:101]
	global_load_lds_dword v[88:89], off
	s_add_u32 s100, s100, 0x10000
	v_lshl_add_u64 v[90:91], v[228:229], 0, s[100:101]
	global_load_lds_dword v[90:91], off
	s_add_u32 s100, s100, 0x10000
	v_lshl_add_u64 v[92:93], v[228:229], 0, s[100:101]
	global_load_lds_dword v[92:93], off
